# weight conversion of the four big matrices as one software-pipelined tile loop (double-buffered LDS and registers)
# speedup vs baseline: 1.0349x; 1.0030x over previous
.LBB0_15:
	s_waitcnt lgkmcnt(0)
	v_writelane_b32 v253, s36, 0
	v_writelane_b32 v253, s37, 1
	v_writelane_b32 v253, s38, 2
	v_writelane_b32 v253, s39, 3
	v_writelane_b32 v253, s40, 4
	v_writelane_b32 v253, s41, 5
	v_writelane_b32 v253, s42, 6
	v_writelane_b32 v253, s43, 7
	v_writelane_b32 v253, s44, 8
	v_writelane_b32 v253, s45, 9
	v_writelane_b32 v253, s46, 10
	v_writelane_b32 v253, s47, 11
	v_writelane_b32 v253, s48, 12
	v_writelane_b32 v253, s49, 13
	v_writelane_b32 v253, s50, 14
	v_writelane_b32 v253, s51, 15
	v_writelane_b32 v253, s52, 16
	v_writelane_b32 v253, s53, 17
	v_writelane_b32 v253, s54, 18
	v_writelane_b32 v253, s55, 19
	v_writelane_b32 v253, s56, 20
	v_writelane_b32 v253, s57, 21
	v_writelane_b32 v253, s58, 22
	v_writelane_b32 v253, s59, 23
	v_writelane_b32 v253, s60, 24
	v_writelane_b32 v253, s61, 25
	v_writelane_b32 v253, s62, 26
	v_writelane_b32 v253, s63, 27
	v_writelane_b32 v253, s64, 28
	v_writelane_b32 v253, s65, 29
	v_writelane_b32 v253, s66, 30
	v_writelane_b32 v253, s67, 31
	s_mov_b64 s[36:37], exec
	v_writelane_b32 v253, s36, 32
	v_writelane_b32 v253, s37, 33
	v_writelane_b32 v253, vcc_lo, 34
	v_writelane_b32 v253, vcc_hi, 35
	s_mov_b64 exec, -1
	s_load_dwordx2 s[36:37], s[0:1], 0x50
	s_load_dwordx2 s[38:39], s[0:1], 0xe8
	s_load_dwordx4 s[40:43], s[0:1], 0xf0
	s_load_dwordx2 s[44:45], s[0:1], 0x108
	s_waitcnt lgkmcnt(0)
	v_and_b32_e32 v200, 15, v156
	v_lshlrev_b32_e32 v200, 4, v200
	v_lshrrev_b32_e32 v201, 4, v156
	v_mul_u32_u24_e32 v202, 0x110, v201
	v_add_u32_e32 v202, v202, v200
	v_lshrrev_b32_e32 v203, 3, v156
	v_and_b32_e32 v204, 7, v156
	v_lshlrev_b32_e32 v204, 4, v204
	v_and_b32_e32 v205, 7, v156
	v_mul_u32_u24_e32 v205, 0x880, v205
	v_lshl_add_u32 v205, v203, 2, v205
	v_add_u32_e32 v206, 0x400, v205
	s_mov_b32 s46, s92
	s_cmp_ge_u32 s46, 0xb70
	s_cbranch_scc1 .LcvA_done
	s_mov_b32 s47, 0
	v_add_u32_e32 v240, 0x4400, v205
	v_add_u32_e32 v241, 0x4400, v206
	s_mov_b32 s62, s46
	s_cmp_lt_u32 s62, 624
	s_cbranch_scc1 .LcvA_ld1_win
	s_cmp_lt_u32 s62, 880
	s_cbranch_scc1 .LcvA_ld1_wout
	s_cmp_lt_u32 s62, 1904
	s_cbranch_scc1 .LcvA_ld1_w1
.LcvA_ld1_w2:
	s_sub_u32 s58, s62, 1904
	s_lshr_b32 s59, s58, 4
	s_and_b32 s55, s58, 15
	s_mov_b64 s[48:49], s[42:43]
	s_movk_i32 s50, 0x1000
	s_mov_b32 s60, 0x1280000
	s_movk_i32 s54, 0x2000
	s_mov_b32 s56, 0x7fffffff
	s_mov_b32 s57, 0x7fffffff
	s_branch .LcvA_ld1_end
.LcvA_ld1_win:
	s_mul_i32 s59, s62, 1681
	s_lshr_b32 s59, s59, 16
	s_mul_i32 s55, s59, 39
	s_sub_u32 s55, s62, s55
	s_mov_b64 s[48:49], s[36:37]
	s_movk_i32 s50, 0x2700
	s_mov_b32 s60, 0x300000
	s_movk_i32 s54, 0x800
	s_movk_i32 s56, 928
	s_movk_i32 s57, 1984
	s_branch .LcvA_ld1_end
.LcvA_ld1_wout:
	s_sub_u32 s58, s62, 624
	s_lshr_b32 s59, s58, 4
	s_and_b32 s55, s58, 15
	s_mov_b64 s[48:49], s[38:39]
	s_movk_i32 s50, 0x1000
	s_mov_b32 s60, 0x880000
	s_movk_i32 s54, 0x800
	s_mov_b32 s56, 0x7fffffff
	s_mov_b32 s57, 0x7fffffff
	s_branch .LcvA_ld1_end
.LcvA_ld1_w1:
	s_sub_u32 s58, s62, 880
	s_lshr_b32 s59, s58, 6
	s_and_b32 s55, s58, 63
	s_mov_b64 s[48:49], s[40:41]
	s_movk_i32 s50, 0x4000
	s_mov_b32 s60, 0xa80000
	s_movk_i32 s54, 0x800
	s_mov_b32 s56, 0x7fffffff
	s_mov_b32 s57, 0x7fffffff
.LcvA_ld1_end:
	s_lshl_b32 s55, s55, 6
	s_lshl_b32 s59, s59, 6
	s_mul_i32 s58, s59, s50
	s_lshl_b32 s61, s55, 2
	s_add_u32 s58, s58, s61
	s_add_u32 s48, s48, s58
	s_addc_u32 s49, s49, 0
	s_lshl_b32 s51, s50, 5
	s_lshl_b32 s61, s59, 1
	s_add_u32 s60, s60, s61
	s_add_u32 s52, s44, s60
	s_addc_u32 s53, s45, 0
	v_mad_u32_u24 v207, v201, s50, v200
	global_load_dwordx4 v[208:211], v207, s[48:49] nt
	s_add_u32 s48, s48, s51
	s_addc_u32 s49, s49, 0
	global_load_dwordx4 v[212:215], v207, s[48:49] nt
.LcvA_loop:
	s_add_u32 s62, s46, 0x100
	s_cmp_ge_u32 s62, 0xb70
	s_cbranch_scc1 .LcvA_nonext0
	s_cmp_lt_u32 s62, 624
	s_cbranch_scc1 .LcvA_ld2_win
	s_cmp_lt_u32 s62, 880
	s_cbranch_scc1 .LcvA_ld2_wout
	s_cmp_lt_u32 s62, 1904
	s_cbranch_scc1 .LcvA_ld2_w1

.LcvA_ld2_end:
	s_lshl_b32 s55, s55, 6
	s_lshl_b32 s59, s59, 6
	s_mul_i32 s58, s59, s50
	s_lshl_b32 s61, s55, 2
	s_add_u32 s58, s58, s61
	s_add_u32 s48, s48, s58
	s_addc_u32 s49, s49, 0
	s_lshl_b32 s51, s50, 5
	s_lshl_b32 s61, s59, 1
	s_add_u32 s60, s60, s61
	s_add_u32 s52, s44, s60
	s_addc_u32 s53, s45, 0
	v_mad_u32_u24 v207, v201, s50, v200
	global_load_dwordx4 v[216:219], v207, s[48:49] nt
	s_add_u32 s48, s48, s51
	s_addc_u32 s49, s49, 0
	global_load_dwordx4 v[220:223], v207, s[48:49] nt
	s_cmp_eq_u32 s47, 0
	s_cbranch_scc1 .LcvA_w2_0
	s_waitcnt vmcnt(3)
	s_branch .LcvA_go0
.LcvA_w2_0:
	s_waitcnt vmcnt(2)
	s_branch .LcvA_go0

.LcvA_go0:
	ds_write_b128 v202, v[208:211]
	ds_write_b128 v202, v[212:215] offset:8704
	s_waitcnt lgkmcnt(0)
	s_barrier
	ds_read2_b32 v[224:225], v205 offset1:68
	ds_read2_b32 v[226:227], v205 offset0:136 offset1:204
	ds_read2_b32 v[228:229], v206 offset0:16 offset1:84
	ds_read2_b32 v[230:231], v206 offset0:152 offset1:220
	s_mov_b32 s62, s46
	s_cmp_lt_u32 s62, 624
	s_cbranch_scc1 .LcvA_st0_win
	s_cmp_lt_u32 s62, 880
	s_cbranch_scc1 .LcvA_st0_wout
	s_cmp_lt_u32 s62, 1904
	s_cbranch_scc1 .LcvA_st0_w1

.LcvA_st0_end:
	s_lshl_b32 s55, s55, 6
	s_lshl_b32 s59, s59, 6
	s_mul_i32 s58, s59, s50
	s_lshl_b32 s61, s55, 2
	s_add_u32 s58, s58, s61
	s_add_u32 s48, s48, s58
	s_addc_u32 s49, s49, 0
	s_lshl_b32 s51, s50, 5
	s_lshl_b32 s61, s59, 1
	s_add_u32 s60, s60, s61
	s_add_u32 s52, s44, s60
	s_addc_u32 s53, s45, 0
	v_add_u32_e32 v236, s55, v203
	v_mov_b32_e32 v237, 0x60
	v_mov_b32_e32 v238, 0xe0
	v_cmp_le_u32_e32 vcc, s56, v236
	s_nop 1
	v_cndmask_b32_e32 v237, 0, v237, vcc
	v_cmp_le_u32_e32 vcc, s57, v236
	s_nop 1
	v_cndmask_b32_e32 v238, 0, v238, vcc
	v_add3_u32 v236, v236, v237, v238
	v_mad_u32_u24 v236, v236, s54, v204
	s_waitcnt lgkmcnt(0)
	v_cvt_pk_bf16_f32 v232, v224, v225
	v_cvt_pk_bf16_f32 v233, v226, v227
	v_cvt_pk_bf16_f32 v234, v228, v229
	v_cvt_pk_bf16_f32 v235, v230, v231
	global_store_dwordx4 v236, v[232:235], s[52:53]
	s_mov_b32 s47, 1
	s_add_u32 s46, s46, 0x100
	s_cmp_ge_u32 s46, 0xb70
	s_cbranch_scc1 .LcvA_done
	s_add_u32 s62, s46, 0x100
	s_cmp_ge_u32 s62, 0xb70
	s_cbranch_scc1 .LcvA_nonext1
	s_cmp_lt_u32 s62, 624
	s_cbranch_scc1 .LcvA_ld3_win
	s_cmp_lt_u32 s62, 880
	s_cbranch_scc1 .LcvA_ld3_wout
	s_cmp_lt_u32 s62, 1904
	s_cbranch_scc1 .LcvA_ld3_w1

.LcvA_ld3_end:
	s_lshl_b32 s55, s55, 6
	s_lshl_b32 s59, s59, 6
	s_mul_i32 s58, s59, s50
	s_lshl_b32 s61, s55, 2
	s_add_u32 s58, s58, s61
	s_add_u32 s48, s48, s58
	s_addc_u32 s49, s49, 0
	s_lshl_b32 s51, s50, 5
	s_lshl_b32 s61, s59, 1
	s_add_u32 s60, s60, s61
	s_add_u32 s52, s44, s60
	s_addc_u32 s53, s45, 0
	v_mad_u32_u24 v207, v201, s50, v200
	global_load_dwordx4 v[208:211], v207, s[48:49] nt
	s_add_u32 s48, s48, s51
	s_addc_u32 s49, s49, 0
	global_load_dwordx4 v[212:215], v207, s[48:49] nt
	s_cmp_eq_u32 s47, 0
	s_cbranch_scc1 .LcvA_w2_1
	s_waitcnt vmcnt(3)
	s_branch .LcvA_go1

.LcvA_go1:
	ds_write_b128 v202, v[216:219] offset:17408
	ds_write_b128 v202, v[220:223] offset:26112
	s_waitcnt lgkmcnt(0)
	s_barrier
	ds_read2_b32 v[224:225], v240 offset1:68
	ds_read2_b32 v[226:227], v240 offset0:136 offset1:204
	ds_read2_b32 v[228:229], v241 offset0:16 offset1:84
	ds_read2_b32 v[230:231], v241 offset0:152 offset1:220
	s_mov_b32 s62, s46
	s_cmp_lt_u32 s62, 624
	s_cbranch_scc1 .LcvA_st1_win
	s_cmp_lt_u32 s62, 880
	s_cbranch_scc1 .LcvA_st1_wout
	s_cmp_lt_u32 s62, 1904
	s_cbranch_scc1 .LcvA_st1_w1

.LcvA_st1_end:
	s_lshl_b32 s55, s55, 6
	s_lshl_b32 s59, s59, 6
	s_mul_i32 s58, s59, s50
	s_lshl_b32 s61, s55, 2
	s_add_u32 s58, s58, s61
	s_add_u32 s48, s48, s58
	s_addc_u32 s49, s49, 0
	s_lshl_b32 s51, s50, 5
	s_lshl_b32 s61, s59, 1
	s_add_u32 s60, s60, s61
	s_add_u32 s52, s44, s60
	s_addc_u32 s53, s45, 0
	v_add_u32_e32 v236, s55, v203
	v_mov_b32_e32 v237, 0x60
	v_mov_b32_e32 v238, 0xe0
	v_cmp_le_u32_e32 vcc, s56, v236
	s_nop 1
	v_cndmask_b32_e32 v237, 0, v237, vcc
	v_cmp_le_u32_e32 vcc, s57, v236
	s_nop 1
	v_cndmask_b32_e32 v238, 0, v238, vcc
	v_add3_u32 v236, v236, v237, v238
	v_mad_u32_u24 v236, v236, s54, v204
	s_waitcnt lgkmcnt(0)
	v_cvt_pk_bf16_f32 v232, v224, v225
	v_cvt_pk_bf16_f32 v233, v226, v227
	v_cvt_pk_bf16_f32 v234, v228, v229
	v_cvt_pk_bf16_f32 v235, v230, v231
	global_store_dwordx4 v236, v[232:235], s[52:53]
	s_mov_b32 s47, 1
	s_add_u32 s46, s46, 0x100
	s_cmp_ge_u32 s46, 0xb70
	s_cbranch_scc1 .LcvA_done
	s_branch .LcvA_loop
.LcvA_done:
	s_waitcnt vmcnt(0) lgkmcnt(0)
	s_barrier
	v_readlane_b32 vcc_lo, v253, 34
	v_readlane_b32 vcc_hi, v253, 35
	v_readlane_b32 s36, v253, 32
	v_readlane_b32 s37, v253, 33
	s_nop 3
	s_mov_b64 exec, s[36:37]
	v_readlane_b32 s36, v253, 0
	v_readlane_b32 s37, v253, 1
	v_readlane_b32 s38, v253, 2
	v_readlane_b32 s39, v253, 3
	v_readlane_b32 s40, v253, 4
	v_readlane_b32 s41, v253, 5
	v_readlane_b32 s42, v253, 6
	v_readlane_b32 s43, v253, 7
	v_readlane_b32 s44, v253, 8
	v_readlane_b32 s45, v253, 9
	v_readlane_b32 s46, v253, 10
	v_readlane_b32 s47, v253, 11
	v_readlane_b32 s48, v253, 12
	v_readlane_b32 s49, v253, 13
	v_readlane_b32 s50, v253, 14
	v_readlane_b32 s51, v253, 15
	v_readlane_b32 s52, v253, 16
	v_readlane_b32 s53, v253, 17
	v_readlane_b32 s54, v253, 18
	v_readlane_b32 s55, v253, 19
	v_readlane_b32 s56, v253, 20
	v_readlane_b32 s57, v253, 21
	v_readlane_b32 s58, v253, 22
	v_readlane_b32 s59, v253, 23
	v_readlane_b32 s60, v253, 24
	v_readlane_b32 s61, v253, 25
	v_readlane_b32 s62, v253, 26
	v_readlane_b32 s63, v253, 27
	v_readlane_b32 s64, v253, 28
	v_readlane_b32 s65, v253, 29
	v_readlane_b32 s66, v253, 30
	v_readlane_b32 s67, v253, 31
	s_nop 3
	s_abs_i32 s19, s28
	v_cvt_f32_u32_e32 v1, s19
	v_mov_b32_e32 v2, v156
	s_mov_b32 s2, s92
	s_sub_i32 s12, 0, s19
	v_rcp_iflag_f32_e32 v1, v1
	s_add_i32 s2, s2, s28
	v_mul_f32_e32 v1, 0x4f7ffffe, v1
	v_cvt_u32_f32_e32 v1, v1
	s_ashr_i32 s3, s2, 31
	s_abs_i32 s2, s2
	v_readfirstlane_b32 s13, v1
	s_mul_i32 s12, s12, s13
	s_mul_hi_u32 s12, s13, s12
	s_add_i32 s12, s13, s12
	v_writelane_b32 v254, s12, 0
	s_mul_hi_u32 s12, s2, s12
	s_mul_i32 s12, s12, s19
	s_sub_i32 s2, s2, s12
	s_sub_i32 s12, s2, s19
	s_cmp_ge_u32 s2, s19
	s_cselect_b32 s2, s12, s2
	s_sub_i32 s12, s2, s19
	s_cmp_ge_u32 s2, s19
	s_cselect_b32 s2, s12, s2
	s_xor_b32 s2, s2, s3
	s_sub_i32 s33, s2, s3
	s_cmpk_gt_i32 s33, 0x26f
	s_branch .LBB0_22
	v_ashrrev_i32_e32 v1, 4, v2
	v_ashrrev_i32_e32 v14, 3, v2
	v_lshlrev_b32_e32 v3, 3, v2
	v_lshlrev_b32_e32 v2, 2, v2
	v_and_b32_e32 v2, 60, v2
	s_movk_i32 s12, 0x110
	v_and_b32_e32 v4, 56, v3
	v_lshlrev_b32_e32 v3, 2, v2
	v_mul_lo_u32 v5, v1, s12
	v_add3_u32 v15, 0, v3, v5
	v_add3_u32 v16, 0, v5, v3
	v_lshl_add_u32 v3, v14, 2, 0
	v_mul_u32_u24_e32 v5, 0x110, v4
	s_add_u32 s2, s22, 0x300000
	v_mov_b32_e32 v11, 0
	v_add_u32_e32 v17, v3, v5
	s_addc_u32 s3, s23, 0
	s_lshl_b32 s38, s33, 6
	s_lshl_b32 s39, s28, 6
	s_movk_i32 s40, 0x400
	s_movk_i32 s41, 0x2700
	s_movk_i32 s42, 0x3e0
	s_movk_i32 s43, 0x7c0
	v_mov_b32_e32 v18, 0x140
	v_mov_b32_e32 v19, 0x60
	s_movk_i32 s44, 0x39f
	v_lshlrev_b32_e32 v12, 1, v4
	v_mov_b32_e32 v13, v11
	v_lshlrev_b32_e32 v10, 2, v2
	v_add_u32_e32 v20, 0x400, v17
	s_branch .LBB0_18

.LBB0_22:
	v_readlane_b32 s13, v254, 0
	s_mul_hi_u32 s3, s13, 0x270
	v_mov_b32_e32 v2, v156
	s_mov_b32 s2, s92
	s_mul_i32 s3, s3, s19
	s_sub_i32 s3, 0x270, s3
	s_add_i32 s2, s2, s28
	s_sub_i32 s12, s3, s19
	s_cmp_ge_u32 s3, s19
	s_cselect_b32 s3, s12, s3
	s_sub_i32 s12, s3, s19
	s_cmp_ge_u32 s3, s19
	s_cselect_b32 s33, s12, s3
	s_sub_i32 s2, s2, s33
	s_ashr_i32 s3, s2, 31
	s_abs_i32 s2, s2
	s_mul_hi_u32 s12, s2, s13
	s_mul_i32 s12, s12, s19
	s_sub_i32 s2, s2, s12
	s_sub_i32 s12, s2, s19
	s_cmp_ge_u32 s2, s19
	s_cselect_b32 s2, s12, s2
	s_sub_i32 s12, s2, s19
	s_cmp_ge_u32 s2, s19
	s_cselect_b32 s2, s12, s2
	s_xor_b32 s2, s2, s3
	s_sub_i32 s36, s2, s3
	s_cmpk_gt_i32 s36, 0xff
	s_branch .LBB0_29
	v_ashrrev_i32_e32 v1, 4, v2
	v_ashrrev_i32_e32 v16, 3, v2
	v_lshlrev_b32_e32 v3, 3, v2
	v_lshlrev_b32_e32 v2, 2, v2
	v_and_b32_e32 v2, 60, v2
	s_movk_i32 s12, 0x110
	v_and_b32_e32 v4, 56, v3
	v_lshlrev_b32_e32 v3, 2, v2
	v_mul_lo_u32 v5, v1, s12
	v_add3_u32 v17, 0, v3, v5
	v_add3_u32 v18, 0, v5, v3
	v_lshl_add_u32 v3, v16, 2, 0
	v_mul_u32_u24_e32 v5, 0x110, v4
	s_add_u32 s2, s22, 0x880000
	v_mov_b32_e32 v11, 0
	v_add_u32_e32 v19, v3, v5
	s_addc_u32 s3, s23, 0
	s_lshl_b32 s37, s36, 6
	s_lshl_b32 s38, s28, 6
	s_movk_i32 s39, 0x400
	s_movk_i32 s40, 0x3e0
	v_lshlrev_b32_e32 v12, 1, v4
	v_mov_b32_e32 v13, v11
	v_lshlrev_b32_e32 v10, 2, v2
	v_add_u32_e32 v20, 0x400, v19
	s_branch .LBB0_25

.LBB0_29:
	v_readlane_b32 s9, v254, 0
	s_mul_hi_u32 s3, s9, 0x370
	v_mov_b32_e32 v2, v156
	s_mov_b32 s2, s92
	s_mul_i32 s3, s3, s19
	s_sub_i32 s3, 0x370, s3
	s_add_i32 s2, s2, s28
	s_sub_i32 s8, s3, s19
	s_cmp_ge_u32 s3, s19
	s_cselect_b32 s3, s8, s3
	s_sub_i32 s8, s3, s19
	s_cmp_ge_u32 s3, s19
	s_cselect_b32 s34, s8, s3
	s_sub_i32 s2, s2, s34
	s_ashr_i32 s3, s2, 31
	s_abs_i32 s2, s2
	s_mul_hi_u32 s8, s2, s9
	s_mul_i32 s8, s8, s19
	s_sub_i32 s2, s2, s8
	s_sub_i32 s8, s2, s19
	s_cmp_ge_u32 s2, s19
	s_cselect_b32 s2, s8, s2
	s_sub_i32 s8, s2, s19
	s_cmp_ge_u32 s2, s19
	s_cselect_b32 s2, s8, s2
	s_xor_b32 s2, s2, s3
	s_sub_i32 s35, s2, s3
	s_cmpk_gt_i32 s35, 0x3ff
	s_branch .LBB0_36
	v_ashrrev_i32_e32 v1, 4, v2
	v_ashrrev_i32_e32 v16, 3, v2
	v_lshlrev_b32_e32 v3, 3, v2
	v_lshlrev_b32_e32 v2, 2, v2
	v_and_b32_e32 v2, 60, v2
	s_movk_i32 s8, 0x110
	v_and_b32_e32 v4, 56, v3
	v_lshlrev_b32_e32 v3, 2, v2
	v_mul_lo_u32 v5, v1, s8
	v_add3_u32 v17, 0, v3, v5
	v_add3_u32 v18, 0, v5, v3
	v_lshl_add_u32 v3, v16, 2, 0
	v_mul_u32_u24_e32 v5, 0x110, v4
	s_add_u32 s2, s22, 0xa80000
	v_mov_b32_e32 v11, 0
	v_add_u32_e32 v19, v3, v5
	s_addc_u32 s3, s23, 0
	s_lshl_b32 s36, s35, 6
	s_lshl_b32 s37, s28, 6
	s_movk_i32 s38, 0x400
	s_movk_i32 s39, 0x3e0
	v_lshlrev_b32_e32 v12, 1, v4
	v_mov_b32_e32 v13, v11
	v_lshlrev_b32_e32 v10, 2, v2
	v_add_u32_e32 v20, 0x400, v19
	s_branch .LBB0_32

.LBB0_36:
	v_readlane_b32 s9, v254, 0
	s_mul_hi_u32 s3, s9, 0x770
	v_mov_b32_e32 v2, v156
	s_mov_b32 s2, s92
	s_mul_i32 s3, s3, s19
	s_sub_i32 s3, 0x770, s3
	s_add_i32 s2, s2, s28
	s_sub_i32 s8, s3, s19
	s_cmp_ge_u32 s3, s19
	s_cselect_b32 s3, s8, s3
	s_sub_i32 s8, s3, s19
	s_cmp_ge_u32 s3, s19
	s_cselect_b32 s35, s8, s3
	s_sub_i32 s2, s2, s35
	s_ashr_i32 s3, s2, 31
	s_abs_i32 s2, s2
	s_mul_hi_u32 s8, s2, s9
	s_mul_i32 s8, s8, s19
	s_sub_i32 s2, s2, s8
	s_sub_i32 s8, s2, s19
	s_cmp_ge_u32 s2, s19
	s_cselect_b32 s2, s8, s2
	s_sub_i32 s8, s2, s19
	s_cmp_ge_u32 s2, s19
	s_cselect_b32 s2, s8, s2
	s_xor_b32 s2, s2, s3
	s_sub_i32 s14, s2, s3
	s_cmpk_gt_i32 s14, 0x3ff
	s_branch .LBB0_43
	v_ashrrev_i32_e32 v1, 4, v2
	v_ashrrev_i32_e32 v16, 3, v2
	v_lshlrev_b32_e32 v3, 3, v2
	v_lshlrev_b32_e32 v2, 2, v2
	v_and_b32_e32 v2, 60, v2
	s_movk_i32 s8, 0x110
	v_and_b32_e32 v4, 56, v3
	v_lshlrev_b32_e32 v3, 2, v2
	v_mul_lo_u32 v5, v1, s8
	v_add3_u32 v17, 0, v3, v5
	v_add3_u32 v18, 0, v5, v3
	v_lshl_add_u32 v3, v16, 2, 0
	v_mul_u32_u24_e32 v5, 0x110, v4
	s_add_u32 s2, s22, 0x1280000
	v_mov_b32_e32 v11, 0
	v_add_u32_e32 v19, v3, v5
	s_addc_u32 s3, s23, 0
	s_lshl_b32 s15, s14, 6
	s_lshl_b32 s36, s28, 6
	s_movk_i32 s37, 0x1000
	s_movk_i32 s38, 0xfe0
	v_lshlrev_b32_e32 v12, 1, v4
	v_mov_b32_e32 v13, v11
	v_lshlrev_b32_e32 v10, 2, v2
	v_add_u32_e32 v20, 0x400, v19
	s_branch .LBB0_39

.LBB0_1444:
	s_or_b64 exec, exec, s[4:5]
	s_waitcnt lgkmcnt(0)
	s_barrier
	s_load_dwordx2 s[50:51], s[0:1], 0x30
	s_load_dwordx2 s[68:69], s[0:1], 0x48
	s_load_dwordx2 s[26:27], s[0:1], 0x108
	s_load_dwordx8 s[4:11], s[0:1], 0xe8
	s_and_b64 vcc, exec, s[2:3]
	s_cbranch_vccnz .LBB0_1452
	s_waitcnt lgkmcnt(0)
	v_writelane_b32 v253, s36, 0
	v_writelane_b32 v253, s37, 1
	v_writelane_b32 v253, s38, 2
	v_writelane_b32 v253, s39, 3
	v_writelane_b32 v253, s40, 4
	v_writelane_b32 v253, s41, 5
	v_writelane_b32 v253, s42, 6
	v_writelane_b32 v253, s43, 7
	v_writelane_b32 v253, s44, 8
	v_writelane_b32 v253, s45, 9
	v_writelane_b32 v253, s46, 10
	v_writelane_b32 v253, s47, 11
	v_writelane_b32 v253, s48, 12
	v_writelane_b32 v253, s49, 13
	v_writelane_b32 v253, s50, 14
	v_writelane_b32 v253, s51, 15
	v_writelane_b32 v253, s52, 16
	v_writelane_b32 v253, s53, 17
	v_writelane_b32 v253, s54, 18
	v_writelane_b32 v253, s55, 19
	v_writelane_b32 v253, s56, 20
	v_writelane_b32 v253, s57, 21
	v_writelane_b32 v253, s58, 22
	v_writelane_b32 v253, s59, 23
	v_writelane_b32 v253, s60, 24
	v_writelane_b32 v253, s61, 25
	v_writelane_b32 v253, s62, 26
	v_writelane_b32 v253, s63, 27
	v_writelane_b32 v253, s64, 28
	v_writelane_b32 v253, s65, 29
	v_writelane_b32 v253, s66, 30
	v_writelane_b32 v253, s67, 31
	s_mov_b64 s[36:37], exec
	v_writelane_b32 v253, s36, 32
	v_writelane_b32 v253, s37, 33
	v_writelane_b32 v253, vcc_lo, 34
	v_writelane_b32 v253, vcc_hi, 35
	s_mov_b64 exec, -1
	s_load_dwordx2 s[36:37], s[0:1], 0x50
	s_load_dwordx2 s[38:39], s[0:1], 0xe8
	s_load_dwordx4 s[40:43], s[0:1], 0xf0
	s_load_dwordx2 s[44:45], s[0:1], 0x108
	s_waitcnt lgkmcnt(0)
	s_add_u32 s36, s36, 0x9c0000
	s_addc_u32 s37, s37, 0
	s_add_u32 s38, s38, 0x400000
	s_addc_u32 s39, s39, 0
	s_add_u32 s40, s40, 0x1000000
	s_addc_u32 s41, s41, 0
	s_add_u32 s42, s42, 0x1000000
	s_addc_u32 s43, s43, 0
	v_and_b32_e32 v200, 15, v156
	v_lshlrev_b32_e32 v200, 4, v200
	v_lshrrev_b32_e32 v201, 4, v156
	v_mul_u32_u24_e32 v202, 0x110, v201
	v_add_u32_e32 v202, v202, v200
	v_lshrrev_b32_e32 v203, 3, v156
	v_and_b32_e32 v204, 7, v156
	v_lshlrev_b32_e32 v204, 4, v204
	v_and_b32_e32 v205, 7, v156
	v_mul_u32_u24_e32 v205, 0x880, v205
	v_lshl_add_u32 v205, v203, 2, v205
	v_add_u32_e32 v206, 0x400, v205
	s_mov_b32 s46, s92
	s_cmp_ge_u32 s46, 0xb70
	s_cbranch_scc1 .LcvB_done
	s_mov_b32 s47, 0
	v_add_u32_e32 v240, 0x4400, v205
	v_add_u32_e32 v241, 0x4400, v206
	s_mov_b32 s62, s46
	s_cmp_lt_u32 s62, 624
	s_cbranch_scc1 .LcvB_ld1_win
	s_cmp_lt_u32 s62, 880
	s_cbranch_scc1 .LcvB_ld1_wout
	s_cmp_lt_u32 s62, 1904
	s_cbranch_scc1 .LcvB_ld1_w1

.LcvB_done:
	s_waitcnt vmcnt(0) lgkmcnt(0)
	s_barrier
	v_readlane_b32 vcc_lo, v253, 34
	v_readlane_b32 vcc_hi, v253, 35
	v_readlane_b32 s36, v253, 32
	v_readlane_b32 s37, v253, 33
	s_nop 3
	s_mov_b64 exec, s[36:37]
	v_readlane_b32 s36, v253, 0
	v_readlane_b32 s37, v253, 1
	v_readlane_b32 s38, v253, 2
	v_readlane_b32 s39, v253, 3
	v_readlane_b32 s40, v253, 4
	v_readlane_b32 s41, v253, 5
	v_readlane_b32 s42, v253, 6
	v_readlane_b32 s43, v253, 7
	v_readlane_b32 s44, v253, 8
	v_readlane_b32 s45, v253, 9
	v_readlane_b32 s46, v253, 10
	v_readlane_b32 s47, v253, 11
	v_readlane_b32 s48, v253, 12
	v_readlane_b32 s49, v253, 13
	v_readlane_b32 s50, v253, 14
	v_readlane_b32 s51, v253, 15
	v_readlane_b32 s52, v253, 16
	v_readlane_b32 s53, v253, 17
	v_readlane_b32 s54, v253, 18
	v_readlane_b32 s55, v253, 19
	v_readlane_b32 s56, v253, 20
	v_readlane_b32 s57, v253, 21
	v_readlane_b32 s58, v253, 22
	v_readlane_b32 s59, v253, 23
	v_readlane_b32 s60, v253, 24
	v_readlane_b32 s61, v253, 25
	v_readlane_b32 s62, v253, 26
	v_readlane_b32 s63, v253, 27
	v_readlane_b32 s64, v253, 28
	v_readlane_b32 s65, v253, 29
	v_readlane_b32 s66, v253, 30
	v_readlane_b32 s67, v253, 31
	s_nop 3
	v_mov_b32_e32 v0, v156
	s_mov_b32 s34, s92
	s_load_dwordx4 s[12:15], s[0:1], 0x78
	s_load_dwordx2 s[74:75], s[0:1], 0x98
	s_load_dwordx2 s[72:73], s[0:1], 0xa8
	s_load_dwordx2 s[70:71], s[0:1], 0xc8
	s_add_i32 s34, s34, s28
	s_ashr_i32 s35, s34, 31
	s_abs_i32 s34, s34
	v_readlane_b32 s37, v254, 0
	s_mul_hi_u32 s37, s34, s37
	s_mul_i32 s37, s37, s19
	s_add_i32 s24, s93, 1
	s_sub_i32 s34, s34, s37
	s_ashr_i32 s25, s24, 31
	s_sub_i32 s37, s34, s19
	s_cmp_ge_u32 s34, s19
	s_cselect_b32 s34, s37, s34
	s_sub_i32 s37, s34, s19
	s_cmp_ge_u32 s34, s19
	s_cselect_b32 s34, s37, s34
	s_xor_b32 s34, s34, s35
	s_sub_i32 s37, s34, s35
	s_cmpk_gt_i32 s37, 0x26f
	s_branch .LBB0_1453
	s_load_dwordx2 s[34:35], s[0:1], 0x50
	s_mul_i32 s43, s24, 0x9c0000
	s_mul_hi_i32 s42, s24, 0x9c0000
	v_ashrrev_i32_e32 v11, 4, v0
	v_ashrrev_i32_e32 v14, 3, v0
	s_waitcnt lgkmcnt(0)
	s_add_u32 s34, s34, s43
	v_lshlrev_b32_e32 v2, 3, v0
	v_lshlrev_b32_e32 v0, 2, v0
	s_addc_u32 s35, s35, s42
	v_and_b32_e32 v10, 60, v0
	s_movk_i32 s42, 0x110
	v_and_b32_e32 v2, 56, v2
	v_lshlrev_b32_e32 v0, 2, v10
	v_mul_lo_u32 v3, v11, s42
	s_add_u32 s78, s26, 0x300000
	v_add3_u32 v15, 0, v0, v3
	v_add3_u32 v16, 0, v3, v0
	v_lshl_add_u32 v0, v14, 2, 0
	v_mul_u32_u24_e32 v3, 0x110, v2
	s_addc_u32 s79, s27, 0
	s_lshl_b32 s42, s37, 6
	v_add_u32_e32 v17, v0, v3
	v_lshlrev_b32_e32 v0, 1, v2
	s_branch .LBB0_1448

.LBB0_1453:
	v_mov_b32_e32 v0, v156
	s_mov_b32 s34, s92
	v_readlane_b32 s35, v254, 4
	s_add_i32 s34, s35, s34
	s_ashr_i32 s35, s34, 31
	s_abs_i32 s34, s34
	v_readlane_b32 s37, v254, 0
	s_mul_hi_u32 s37, s34, s37
	s_mul_i32 s37, s37, s19
	s_sub_i32 s34, s34, s37
	s_sub_i32 s37, s34, s19
	s_cmp_ge_u32 s34, s19
	s_cselect_b32 s34, s37, s34
	s_sub_i32 s37, s34, s19
	s_cmp_ge_u32 s34, s19
	s_cselect_b32 s34, s37, s34
	s_xor_b32 s34, s34, s35
	s_sub_i32 s37, s34, s35
	s_cmpk_gt_i32 s37, 0xff
	s_branch .LBB0_1460
	s_lshl_b64 s[34:35], s[24:25], 22
	v_ashrrev_i32_e32 v11, 4, v0
	v_ashrrev_i32_e32 v16, 3, v0
	v_lshlrev_b32_e32 v2, 3, v0
	v_lshlrev_b32_e32 v0, 2, v0
	s_waitcnt lgkmcnt(0)
	s_add_u32 s4, s4, s34
	v_and_b32_e32 v10, 60, v0
	s_movk_i32 s42, 0x110
	s_addc_u32 s5, s5, s35
	v_and_b32_e32 v2, 56, v2
	v_lshlrev_b32_e32 v0, 2, v10
	v_mul_lo_u32 v3, v11, s42
	s_add_u32 s34, s26, 0x880000
	v_add3_u32 v17, 0, v0, v3
	v_add3_u32 v18, 0, v3, v0
	v_lshl_add_u32 v0, v16, 2, 0
	v_mul_u32_u24_e32 v3, 0x110, v2
	s_addc_u32 s35, s27, 0
	s_lshl_b32 s42, s37, 6
	v_add_u32_e32 v19, v0, v3
	v_lshlrev_b32_e32 v0, 1, v2
	s_branch .LBB0_1456

.LBB0_1460:
	v_mov_b32_e32 v0, v156
	s_mov_b32 s34, s92
	v_readlane_b32 s35, v254, 5
	s_add_i32 s34, s35, s34
	s_ashr_i32 s35, s34, 31
	s_abs_i32 s34, s34
	v_readlane_b32 s37, v254, 0
	s_mul_hi_u32 s37, s34, s37
	s_mul_i32 s37, s37, s19
	s_sub_i32 s34, s34, s37
	s_waitcnt lgkmcnt(0)
	s_lshl_b64 s[4:5], s[24:25], 24
	s_sub_i32 s37, s34, s19
	s_cmp_ge_u32 s34, s19
	s_cselect_b32 s34, s37, s34
	s_sub_i32 s37, s34, s19
	s_cmp_ge_u32 s34, s19
	s_cselect_b32 s34, s37, s34
	s_xor_b32 s34, s34, s35
	s_sub_i32 s37, s34, s35
	s_cmpk_gt_i32 s37, 0x3ff
	s_branch .LBB0_1467
	v_ashrrev_i32_e32 v11, 4, v0
	v_ashrrev_i32_e32 v16, 3, v0
	v_lshlrev_b32_e32 v2, 3, v0
	v_lshlrev_b32_e32 v0, 2, v0
	s_add_u32 s6, s6, s4
	v_and_b32_e32 v10, 60, v0
	s_movk_i32 s42, 0x110
	s_addc_u32 s7, s7, s5
	v_and_b32_e32 v2, 56, v2
	v_lshlrev_b32_e32 v0, 2, v10
	v_mul_lo_u32 v3, v11, s42
	s_add_u32 s34, s26, 0xa80000
	v_add3_u32 v17, 0, v0, v3
	v_add3_u32 v18, 0, v3, v0
	v_lshl_add_u32 v0, v16, 2, 0
	v_mul_u32_u24_e32 v3, 0x110, v2
	s_addc_u32 s35, s27, 0
	s_lshl_b32 s42, s37, 6
	v_add_u32_e32 v19, v0, v3
	v_lshlrev_b32_e32 v0, 1, v2
	s_branch .LBB0_1463

.LBB0_1467:
	v_mov_b32_e32 v0, v156
	s_mov_b32 s6, s92
	v_readlane_b32 s7, v254, 6
	s_add_i32 s6, s7, s6
	s_ashr_i32 s7, s6, 31
	s_abs_i32 s6, s6
	v_readlane_b32 s34, v254, 0
	s_mul_hi_u32 s34, s6, s34
	s_mul_i32 s34, s34, s19
	s_sub_i32 s6, s6, s34
	s_sub_i32 s34, s6, s19
	s_cmp_ge_u32 s6, s19
	s_cselect_b32 s6, s34, s6
	s_sub_i32 s34, s6, s19
	s_cmp_ge_u32 s6, s19
	s_cselect_b32 s6, s34, s6
	s_xor_b32 s6, s6, s7
	s_sub_i32 s37, s6, s7
	s_cmpk_gt_i32 s37, 0x3ff
	s_branch .LBB0_1474
	v_ashrrev_i32_e32 v11, 4, v0
	v_ashrrev_i32_e32 v16, 3, v0
	v_lshlrev_b32_e32 v2, 3, v0
	v_lshlrev_b32_e32 v0, 2, v0
	s_add_u32 s4, s8, s4
	v_and_b32_e32 v10, 60, v0
	s_movk_i32 s8, 0x110
	s_addc_u32 s5, s9, s5
	v_and_b32_e32 v2, 56, v2
	v_lshlrev_b32_e32 v0, 2, v10
	v_mul_lo_u32 v3, v11, s8
	s_add_u32 s6, s26, 0x1280000
	v_add3_u32 v17, 0, v0, v3
	v_add3_u32 v18, 0, v3, v0
	v_lshl_add_u32 v0, v16, 2, 0
	v_mul_u32_u24_e32 v3, 0x110, v2
	s_addc_u32 s7, s27, 0
	s_lshl_b32 s42, s37, 6
	v_add_u32_e32 v19, v0, v3
	v_lshlrev_b32_e32 v0, 1, v2
	s_branch .LBB0_1470
